# address-space specialization: the 27 flat_store in oddnorm, scan2 and the scan tails issued as global_store (no LDS-aperture path, no lgkmcnt traffic)
# baseline (speedup 1.0000x reference)
; #define GAS __attribute__((address_space(1)))
; __device__ __forceinline__ unsigned pk2(float lo, float hi) { f32x2v v = {lo, hi}; bf16x2v b = __builtin_convertvector(v, bf16x2v); return __builtin_bit_cast(unsigned, b); }
; #define GAS __attribute__((address_space(1)))
; DI float bflo(unsigned w) { return __uint_as_float(w << 16); }
; DI float bfhi(unsigned w) { return __uint_as_float(w & 0xffff0000u); }
; template <int MASK> DI float swz_xor(float v) { return __int_as_float(__builtin_amdgcn_ds_swizzle(__float_as_int(v), (MASK << 10) | 0x1f)); }
; DI float bf1(const bf16_t* p) { return __uint_as_float((unsigned)(*(GAS const bf16_t*)p) << 16); }
; DI void phase_oddnorm(const bf16_t* U2, const float* qn, const float* kvn, const float* cs, const float* sn, bf16_t* CQN, bf16_t* CKVN, bf16_t* K) {
;     ...
;     for (int row = gw; row < M; row += nw) {
;         const bf16_t* u = U2 + (size_t)row * 768; const int t = row % TT;
;         GAS const unsigned* uq = (GAS const unsigned*)(u + lane * 6); const unsigned w0 = uq[0], w1 = uq[1], w2 = uq[2];
;         float q[6] = {bflo(w0), bfhi(w0), bflo(w1), bfhi(w1), bflo(w2), bfhi(w2)};
;         float ss = 0.f;
; #pragma unroll
;         for (int e = 0; e < 6; ++e) ss += q[e] * q[e];
;         const float rq = rsqrtf(wave_sum(ss) * (1.f / 384) + EPS);
;         GAS unsigned* oq = (GAS unsigned*)(CQN + (size_t)row * 384 + lane * 6);
;         oq[0] = pk2(q[0] * rq * gq[0], q[1] * rq * gq[1]); oq[1] = pk2(q[2] * rq * gq[2], q[3] * rq * gq[3]); oq[2] = pk2(q[4] * rq * gq[4], q[5] * rq * gq[5]);
;         const u32x2 kw = *(GAS const u32x2*)(u + 384 + lane * 4);
;         float kv[4] = {bflo(kw.x), bfhi(kw.x), bflo(kw.y), bfhi(kw.y)};
;         float s2 = (kv[0] * kv[0] + kv[1] * kv[1]) + (kv[2] * kv[2] + kv[3] * kv[3]);
;         const float rk = rsqrtf(wave_sum(s2) * (1.f / 256) + EPS);
;         u32x2 ow; ow.x = pk2(kv[0] * rk * gk[0], kv[1] * rk * gk[1]); ow.y = pk2(kv[2] * rk * gk[2], kv[3] * rk * gk[3]);
;         *(GAS u32x2*)(CKVN + (size_t)row * 256 + lane * 4) = ow;
;         const float x = bf1(u + 640 + (lane & 31)); const float xp = swz_xor<16>(x);
;         const float c = cs[t * 16 + (lane & 15)], s = sn[t * 16 + (lane & 15)];
;         const float o = (lane & 16) ? (x * c + xp * s) : (x * c - xp * s);
;         const bf16_t ob = tobf(o);
;         if (lane < 32) {
.LBB0_99:
	v_mov_b64_e32 v[24:25], s[38:39]
	s_movk_i32 s10, 0x600
	v_mad_i64_i32 v[28:29], s[10:11], v8, s10, v[24:25]
	v_lshl_add_u64 v[24:25], v[28:29], 0, v[64:65]
	global_load_dwordx3 v[24:26], v[24:25], off
	v_lshl_add_u64 v[54:55], v[28:29], 0, v[58:59]
	global_load_dwordx2 v[54:55], v[54:55], off offset:768
	v_lshl_add_u64 v[56:57], v[28:29], 0, v[60:61]
	global_load_ushort v56, v[56:57], off offset:1280
	s_waitcnt vmcnt(0)
	v_lshlrev_b32_e32 v30, 16, v24
	v_and_b32_e32 v31, 0xffff0000, v24
	v_lshlrev_b32_e32 v24, 16, v25
	v_and_b32_e32 v25, 0xffff0000, v25
	v_lshlrev_b32_e32 v32, 16, v26
	v_and_b32_e32 v33, 0xffff0000, v26
	v_pk_mul_f32 v[26:27], v[30:31], v[30:31]
	v_pk_mul_f32 v[34:35], v[24:25], v[24:25]
	v_add_f32_e32 v9, v26, v27
	v_add_f32_e32 v9, v9, v34
	v_pk_mul_f32 v[36:37], v[32:33], v[32:33]
	v_add_f32_e32 v9, v35, v9
	v_add_f32_e32 v9, v36, v9
	v_add_f32_e32 v9, v37, v9
	s_waitcnt lgkmcnt(0)
	ds_swizzle_b32 v19, v9 offset:swizzle(SWAP,1)
	v_mad_i64_i32 v[34:35], s[10:11], v8, s66, v[12:13]
	s_waitcnt lgkmcnt(0)
	v_add_f32_e32 v9, v9, v19
	ds_swizzle_b32 v19, v9 offset:swizzle(SWAP,2)
	s_waitcnt lgkmcnt(0)
	v_add_f32_e32 v9, v9, v19
	ds_swizzle_b32 v19, v9 offset:swizzle(SWAP,4)
	s_waitcnt lgkmcnt(0)
	v_add_f32_e32 v9, v9, v19
	ds_swizzle_b32 v19, v9 offset:swizzle(SWAP,8)
	s_waitcnt lgkmcnt(0)
	v_add_f32_e32 v9, v9, v19
	ds_swizzle_b32 v19, v9 offset:swizzle(SWAP,16)
	s_waitcnt lgkmcnt(0)
	v_add_f32_e32 v9, v9, v19
	v_mov_b32_e32 v19, v9
	s_nop 1
	v_permlane32_swap_b32_e32 v9, v19
	v_add_f32_e32 v9, v9, v19
	v_fmamk_f32 v9, v9, 0x3b2aaaab, v156
	v_mul_f32_e32 v19, 0x4b800000, v9
	v_cmp_gt_f32_e32 vcc, s90, v9
	s_nop 1
	v_cndmask_b32_e32 v9, v9, v19, vcc
	v_rsq_f32_e32 v9, v9
	v_mov_b32_e32 v19, v65
	v_lshl_add_u64 v[36:37], v[28:29], 0, v[18:19]
	v_mul_f32_e32 v19, 0x45800000, v9
	v_cndmask_b32_e32 v26, v9, v19, vcc
	v_pk_mul_f32 v[30:31], v[26:27], v[30:31] op_sel_hi:[0,1]
	v_pk_mul_f32 v[24:25], v[26:27], v[24:25] op_sel_hi:[0,1]
	v_pk_mul_f32 v[26:27], v[26:27], v[32:33] op_sel_hi:[0,1]
	v_pk_mul_f32 v[30:31], v[0:1], v[30:31]
	v_pk_mul_f32 v[32:33], v[2:3], v[24:25]
	v_pk_mul_f32 v[26:27], v[10:11], v[26:27]
	v_cvt_pk_bf16_f32 v24, v30, v31
	v_cvt_pk_bf16_f32 v25, v32, v33
	v_cvt_pk_bf16_f32 v26, v26, v27
	global_store_dwordx3 v[34:35], v[24:26], off
	s_nop 1
	v_mov_b32_e32 v24, v54
	v_mov_b32_e32 v25, v55
	v_and_b32_e32 v27, 0xffff0000, v25
	v_lshlrev_b32_e32 v26, 16, v25
	v_lshlrev_b32_e32 v30, 16, v24
	v_and_b32_e32 v31, 0xffff0000, v24
	v_pk_mul_f32 v[24:25], v[26:27], v[26:27]
	v_pk_mul_f32 v[32:33], v[30:31], v[30:31]
	v_add_f32_e32 v9, v24, v25
	v_add_f32_e32 v19, v32, v33
	v_add_f32_e32 v9, v19, v9
	ds_swizzle_b32 v19, v9 offset:swizzle(SWAP,1)
	s_waitcnt lgkmcnt(0)
	v_add_f32_e32 v9, v9, v19
	ds_swizzle_b32 v19, v9 offset:swizzle(SWAP,2)
	s_waitcnt lgkmcnt(0)
	v_add_f32_e32 v9, v9, v19
	ds_swizzle_b32 v19, v9 offset:swizzle(SWAP,4)
	s_waitcnt lgkmcnt(0)
	v_add_f32_e32 v9, v9, v19
	ds_swizzle_b32 v19, v9 offset:swizzle(SWAP,8)
	s_waitcnt lgkmcnt(0)
	v_add_f32_e32 v19, v9, v19
	ds_swizzle_b32 v21, v19 offset:swizzle(SWAP,16)
	v_ashrrev_i32_e32 v9, 31, v8
	v_lshlrev_b64 v[24:25], 9, v[8:9]
	v_lshl_add_u64 v[24:25], v[14:15], 0, v[24:25]
	s_waitcnt lgkmcnt(0)
	v_add_f32_e32 v19, v19, v21
	v_mov_b32_e32 v21, v19
	s_nop 1
	v_permlane32_swap_b32_e32 v19, v21
	v_add_f32_e32 v19, v19, v21
	v_fmamk_f32 v19, v19, 0x3b800000, v156
	v_mul_f32_e32 v21, 0x4b800000, v19
	v_cmp_gt_f32_e32 vcc, s90, v19
	s_nop 1
	v_cndmask_b32_e32 v19, v19, v21, vcc
	v_rsq_f32_e32 v19, v19
	v_mov_b32_e32 v21, v65
	v_mul_f32_e32 v9, 0x45800000, v19
	v_cndmask_b32_e32 v32, v19, v9, vcc
	v_pk_mul_f32 v[30:31], v[32:33], v[30:31] op_sel_hi:[0,1]
	v_pk_mul_f32 v[26:27], v[32:33], v[26:27] op_sel_hi:[0,1]
	v_pk_mul_f32 v[30:31], v[4:5], v[30:31]
	v_pk_mul_f32 v[26:27], v[6:7], v[26:27]
	v_cvt_pk_bf16_f32 v30, v30, v31
	v_cvt_pk_bf16_f32 v31, v26, v27
	global_store_dwordx2 v[24:25], v[30:31], off
	v_mov_b32_e32 v9, v56
	v_lshlrev_b32_e32 v9, 16, v9
	ds_swizzle_b32 v19, v9 offset:swizzle(SWAP,16)
	s_and_saveexec_b64 s[34:35], s[8:9]
	s_cbranch_execz .LBB0_98
; template <int MASK> DI float swz_xor(float v) { return __int_as_float(__builtin_amdgcn_ds_swizzle(__float_as_int(v), (MASK << 10) | 0x1f)); }
; DI float bf1(const bf16_t* p) { return __uint_as_float((unsigned)(*(GAS const bf16_t*)p) << 16); }
; DI bf16_t tobf(float f) { return (bf16_t)(pk2(f, 0.f) & 0xffffu); }
; DI void phase_oddnorm(const bf16_t* U2, const float* qn, const float* kvn, const float* cs, const float* sn, bf16_t* CQN, bf16_t* CKVN, bf16_t* K) {
;     ...
;         const float x = bf1(u + 640 + (lane & 31)); const float xp = swz_xor<16>(x);
;         const float c = cs[t * 16 + (lane & 15)], s = sn[t * 16 + (lane & 15)];
;         const float o = (lane & 16) ? (x * c + xp * s) : (x * c - xp * s);
;         const bf16_t ob = tobf(o);
;         if (lane < 32) {
;             const int b_ = row / TT; bf16_t* kp = K + ((size_t)(b_ * 16) * TT + t) * 96 + 64 + lane;
; #pragma unroll
;             for (int h = 0; h < 16; ++h) kp[(size_t)h * TT * 96] = ob;
;         }
	v_mul_hi_i32 v21, v8, s85
	v_lshrrev_b32_e32 v23, 31, v21
	v_ashrrev_i32_e32 v21, 11, v21
	v_add_u32_e32 v21, v21, v23
	v_mul_i32_i24_e32 v23, 0x1010, v21
	v_lshlrev_b32_e32 v24, 4, v23
	v_sub_u32_e32 v24, v22, v24
	v_ashrrev_i32_e32 v25, 31, v24
	v_readlane_b32 s10, v254, 26
	v_lshlrev_b64 v[24:25], 2, v[24:25]
	v_readlane_b32 s11, v254, 27
	v_lshlrev_b32_e32 v21, 4, v21
	s_mov_b32 s12, 0x787000
	v_lshl_add_u64 v[26:27], s[10:11], 0, v[24:25]
	v_readlane_b32 s10, v254, 24
	flat_load_dword v52, v[26:27]
	v_readlane_b32 s11, v254, 25
	s_nop 1
	v_lshl_add_u64 v[24:25], s[10:11], 0, v[24:25]
	flat_load_dword v53, v[24:25]
	v_sub_u32_e32 v24, v8, v23
	v_mul_hi_i32_i24_e32 v27, 0x1010, v21
	v_mul_i32_i24_e32 v26, 0x1010, v21
	v_ashrrev_i32_e32 v25, 31, v24
	v_lshl_add_u64 v[24:25], v[26:27], 0, v[24:25]
	v_mad_u64_u32 v[26:27], s[10:11], v24, s71, v[16:17]
	v_mov_b32_e32 v24, v27
	s_mov_b32 s10, 0x6c6000
	v_add_co_u32_e32 v28, vcc, s10, v26
	v_mad_u64_u32 v[24:25], s[10:11], v25, s71, v[24:25]
	s_mov_b64 s[10:11], vcc
	v_add_co_u32_e32 v30, vcc, s12, v26
	s_mov_b32 s12, 0xc0000
	v_add_co_u32_e64 v32, s[12:13], s12, v26
	v_addc_co_u32_e64 v29, s[10:11], 0, v24, s[10:11]
	s_nop 0
	v_addc_co_u32_e64 v33, s[12:13], 0, v24, s[12:13]
	s_mov_b32 s12, 0x181000
	s_nop 0
	v_add_co_u32_e64 v34, s[12:13], s12, v26
	v_addc_co_u32_e32 v31, vcc, 0, v24, vcc
	s_nop 0
	v_addc_co_u32_e64 v35, s[12:13], 0, v24, s[12:13]
	s_mov_b32 s12, 0x242000
	s_nop 0
	v_add_co_u32_e64 v36, s[12:13], s12, v26
	s_mov_b32 s10, 0x848000
	s_nop 0
	v_addc_co_u32_e64 v37, s[12:13], 0, v24, s[12:13]
	s_mov_b32 s12, 0x303000
	s_nop 0
	v_add_co_u32_e64 v38, s[12:13], s12, v26
	v_add_co_u32_e32 v48, vcc, s10, v26
	s_nop 0
	v_addc_co_u32_e64 v39, s[12:13], 0, v24, s[12:13]
	s_mov_b32 s12, 0x3c3000
	s_nop 0
	v_add_co_u32_e64 v40, s[12:13], s12, v26
	v_addc_co_u32_e32 v49, vcc, 0, v24, vcc
	s_nop 0
	v_addc_co_u32_e64 v41, s[12:13], 0, v24, s[12:13]
	s_mov_b32 s12, 0x484000
	s_nop 0
	v_add_co_u32_e64 v42, s[12:13], s12, v26
	v_add_co_u32_e32 v50, vcc, 0x909000, v26
	s_nop 0
	v_addc_co_u32_e64 v43, s[12:13], 0, v24, s[12:13]
	s_mov_b32 s12, 0x545000
	s_nop 0
	v_add_co_u32_e64 v44, s[12:13], s12, v26
	v_mov_b32_e32 v27, v24
	s_nop 0
	v_addc_co_u32_e64 v45, s[12:13], 0, v24, s[12:13]
	s_mov_b32 s12, 0x606000
	s_nop 0
	v_add_co_u32_e64 v46, s[12:13], s12, v26
	v_addc_co_u32_e32 v51, vcc, 0, v24, vcc
	s_nop 0
	v_addc_co_u32_e64 v47, s[12:13], 0, v24, s[12:13]
	s_waitcnt vmcnt(0) lgkmcnt(0)
	v_mul_f32_e32 v19, v52, v19
	v_cndmask_b32_e64 v19, v19, -v19, s[6:7]
	v_fmac_f32_e32 v19, v53, v9
	v_cvt_pk_bf16_f32 v9, v19, s0
	global_store_short v[26:27], v9, off offset:128
	global_store_short v[32:33], v9, off offset:3200
	global_store_short v[34:35], v9, off offset:2176
	global_store_short v[36:37], v9, off offset:1152
	global_store_short v[38:39], v9, off offset:128
	global_store_short v[40:41], v9, off offset:3200
	global_store_short v[42:43], v9, off offset:2176
	global_store_short v[44:45], v9, off offset:1152
	global_store_short v[46:47], v9, off offset:128
	global_store_short v[28:29], v9, off offset:3200
	global_store_short v[30:31], v9, off offset:2176
	global_store_short v[48:49], v9, off offset:1152
	global_store_short v[50:51], v9, off offset:128
	v_add_co_u32_e32 v28, vcc, 0x9c9000, v26
	s_nop 1
	v_addc_co_u32_e32 v29, vcc, 0, v24, vcc
	global_store_short v[28:29], v9, off offset:3200
	v_add_co_u32_e32 v28, vcc, 0xa8a000, v26
	s_nop 1
	v_addc_co_u32_e32 v29, vcc, 0, v24, vcc
	v_add_co_u32_e32 v26, vcc, 0xb4b000, v26
	global_store_short v[28:29], v9, off offset:2176
	s_nop 0
	v_addc_co_u32_e32 v27, vcc, 0, v24, vcc
	global_store_short v[26:27], v9, off offset:1152
	s_branch .LBB0_98

; DI float bf1(const bf16_t* p) { return __uint_as_float((unsigned)(*(GAS const bf16_t*)p) << 16); }
; DI bf16_t tobf(float f) { return (bf16_t)(pk2(f, 0.f) & 0xffffu); }
; DI float gelu_tanh(float x) { const float u = 0.7978845608028654f * (x + 0.044715f * x * x * x); const float e = __expf(2.f * u); const float th = 1.f - 2.f / (e + 1.f); return 0.5f * x * (1.f + th); }
; DI void phase_scan2(const bf16_t* A, const bf16_t* U, const float* agg, const bf16_t* GATE, bf16_t* Y) {
;     ...
;         for (int s0 = 0; s0 < 256; s0 += 8) {
;             float a[8], u[8], g[8];
; #pragma unroll
;             for (int e = 0; e < 8; ++e) { a[e] = bf1(A + base + (size_t)(s0 + e) * 512); u[e] = bf1(U + base + (size_t)(s0 + e) * 512); g[e] = bf1(GATE + base + (size_t)(s0 + e) * 512); }
; #pragma unroll
;             for (int e = 0; e < 8; ++e) { h = __expf(a[e]) * h + u[e]; Y[(row0 + s0 + e) * 1024 + 512 + ch] = tobf(gelu_tanh(g[e]) * h); }
;         }
.LBB0_124:
	s_mov_b64 s[6:7], 0x4000
	v_lshl_add_u64 v[16:17], s[24:25], 0, v[8:9]
	s_waitcnt lgkmcnt(0)
	v_lshl_add_u64 v[18:19], s[24:25], 0, v[6:7]
	v_lshl_add_u64 v[6:7], v[6:7], 0, s[6:7]
	s_mov_b32 s6, 0x16901000
	v_add_co_u32_e64 v24, s[6:7], s6, v16
	v_add_co_u32_e32 v22, vcc, 0x16900000, v16
	s_nop 0
	v_addc_co_u32_e64 v25, s[6:7], 0, v17, s[6:7]
	s_mov_b32 s6, 0x1e981000
	s_nop 0
	v_add_co_u32_e64 v26, s[6:7], s6, v16
	v_addc_co_u32_e32 v23, vcc, 0, v17, vcc
	s_nop 0
	v_addc_co_u32_e64 v27, s[6:7], 0, v17, s[6:7]
	s_mov_b32 s6, 0x26a01000
	s_nop 0
	v_add_co_u32_e64 v28, s[6:7], s6, v16
	s_add_i32 s42, s42, 8
	s_nop 0
	v_addc_co_u32_e64 v29, s[6:7], 0, v17, s[6:7]
	global_load_ushort v21, v[26:27], off
	global_load_ushort v30, v[28:29], off
	global_load_ushort v31, v[26:27], off offset:1024
	global_load_ushort v32, v[28:29], off offset:1024
	global_load_ushort v33, v[26:27], off offset:2048
	global_load_ushort v34, v[28:29], off offset:2048
	s_nop 0
	global_load_ushort v28, v[28:29], off offset:3072
	s_nop 0
	global_load_ushort v29, v[26:27], off offset:3072
	global_load_ushort v35, v[22:23], off
	global_load_ushort v36, v[22:23], off offset:1024
	global_load_ushort v37, v[22:23], off offset:2048
	v_add_co_u32_e32 v26, vcc, 0x1e980000, v16
	s_mov_b32 s6, 0x2ec00000
	s_nop 0
	v_addc_co_u32_e32 v27, vcc, 0, v17, vcc
	global_load_ushort v38, v[26:27], off
	global_load_ushort v39, v[26:27], off offset:1024
	global_load_ushort v40, v[26:27], off offset:2048
	s_nop 0
	global_load_ushort v26, v[26:27], off offset:3072
	s_nop 0
	global_load_ushort v22, v[22:23], off offset:3072
	v_add_co_u32_e32 v16, vcc, 0x26a00000, v16
	v_add_co_u32_e64 v14, s[6:7], s6, v18
	s_nop 0
	v_addc_co_u32_e32 v17, vcc, 0, v17, vcc
	global_load_ushort v23, v[16:17], off
	global_load_ushort v27, v[16:17], off offset:1024
	global_load_ushort v41, v[16:17], off offset:2048
	s_nop 0
	global_load_ushort v16, v[16:17], off offset:3072
	s_nop 0
	global_load_ushort v17, v[24:25], off
	global_load_ushort v42, v[24:25], off offset:1024
	global_load_ushort v43, v[24:25], off offset:2048
	s_nop 0
	global_load_ushort v24, v[24:25], off offset:3072
	v_addc_co_u32_e64 v15, s[6:7], 0, v19, s[6:7]
	s_mov_b32 s6, 0x2ec01000
	s_nop 0
	v_add_co_u32_e64 v12, s[6:7], s6, v18
	v_lshl_add_u64 v[8:9], v[8:9], 0, s[74:75]
	s_nop 0
	v_addc_co_u32_e64 v13, s[6:7], 0, v19, s[6:7]
	s_mov_b32 s6, 0x2ec02000
	s_nop 0
	v_add_co_u32_e64 v10, s[6:7], s6, v18
	s_cmpk_lt_u32 s42, 0xf8
	s_nop 0
	v_addc_co_u32_e64 v11, s[6:7], 0, v19, s[6:7]
	s_mov_b32 s6, 0x2ec03000
	s_nop 0
	v_add_co_u32_e64 v18, s[6:7], s6, v18
	s_waitcnt vmcnt(0)
	v_lshlrev_b32_e32 v21, 16, v21
	v_lshlrev_b32_e32 v25, 16, v30
	v_lshlrev_b32_e32 v30, 16, v31
	v_lshlrev_b32_e32 v31, 16, v32
	v_lshlrev_b32_e32 v32, 16, v33
	v_lshlrev_b32_e32 v33, 16, v34
	v_lshlrev_b32_e32 v34, 16, v35
	v_lshlrev_b32_e32 v35, 16, v36
	v_lshlrev_b32_e32 v36, 16, v37
	v_mul_f32_e32 v37, 0x3d372713, v25
	v_mul_f32_e32 v45, 0x3d372713, v31
	v_mul_f32_e32 v47, 0x3d372713, v33
	v_lshlrev_b32_e32 v28, 16, v28
	v_mul_f32_e32 v34, 0x3fb8aa3b, v34
	v_mul_f32_e32 v37, v37, v25
	v_mul_f32_e32 v45, v45, v31
	v_mul_f32_e32 v47, v47, v33
	v_lshlrev_b32_e32 v23, 16, v23
	v_mul_f32_e32 v44, 0.5, v25
	v_mul_f32_e32 v46, 0.5, v31
	v_mul_f32_e32 v48, 0.5, v33
	v_mul_f32_e32 v49, 0x3d372713, v28
	v_mul_f32_e32 v35, 0x3fb8aa3b, v35
	v_lshlrev_b32_e32 v27, 16, v27
	v_exp_f32_e32 v34, v34
	v_fma_f32 v25, v37, v25, v25
	v_fma_f32 v31, v45, v31, v31
	v_fma_f32 v33, v47, v33, v33
	v_mul_f32_e32 v37, 0x3d372713, v23
	v_lshlrev_b32_e32 v22, 16, v22
	v_mul_f32_e32 v36, 0x3fb8aa3b, v36
	v_mul_f32_e32 v49, v49, v28
	v_lshlrev_b32_e32 v41, 16, v41
	v_exp_f32_e32 v35, v35
	v_mul_f32_e32 v47, 0x3d372713, v27
	v_mul_f32_e32 v25, 0x3f4c422a, v25
	v_mul_f32_e32 v31, 0x3f4c422a, v31
	v_mul_f32_e32 v33, 0x3f4c422a, v33
	v_mul_f32_e32 v37, v37, v23
	v_mul_f32_e32 v50, 0.5, v28
	v_lshlrev_b32_e32 v16, 16, v16
	v_lshlrev_b32_e32 v17, 16, v17
	v_exp_f32_e32 v36, v36
	v_mul_f32_e32 v22, 0x3fb8aa3b, v22
	v_fma_f32 v28, v49, v28, v28
	v_mul_f32_e32 v45, 0.5, v23
	v_mul_f32_e32 v51, 0x3d372713, v41
	v_mul_f32_e32 v47, v47, v27
	v_add_f32_e32 v25, v25, v25
	v_add_f32_e32 v31, v31, v31
	v_add_f32_e32 v33, v33, v33
	v_fma_f32 v23, v37, v23, v23
	v_lshlrev_b32_e32 v38, 16, v38
	v_lshlrev_b32_e32 v42, 16, v42
	v_mul_f32_e32 v49, 0.5, v27
	v_exp_f32_e32 v22, v22
	v_mul_f32_e32 v53, 0x3d372713, v16
	v_mul_f32_e32 v17, 0x3fb8aa3b, v17
	v_mul_f32_e32 v28, 0x3f4c422a, v28
	v_mul_f32_e32 v51, v51, v41
	v_fma_f32 v27, v47, v27, v27
	v_mul_f32_e32 v25, 0x3fb8aa3b, v25
	v_mul_f32_e32 v31, 0x3fb8aa3b, v31
	v_mul_f32_e32 v33, 0x3fb8aa3b, v33
	v_mul_f32_e32 v23, 0x3f4c422a, v23
	v_lshlrev_b32_e32 v39, 16, v39
	v_lshlrev_b32_e32 v43, 16, v43
	v_mul_f32_e32 v42, 0x3fb8aa3b, v42
	v_mul_f32_e32 v53, v53, v16
	v_exp_f32_e32 v17, v17
	v_add_f32_e32 v28, v28, v28
	v_fma_f32 v37, v51, v41, v41
	v_fmac_f32_e32 v38, v20, v34
	v_mul_f32_e32 v27, 0x3f4c422a, v27
	v_exp_f32_e32 v25, v25
	v_exp_f32_e32 v31, v31
	v_exp_f32_e32 v33, v33
	v_add_f32_e32 v23, v23, v23
	v_lshlrev_b32_e32 v29, 16, v29
	v_lshlrev_b32_e32 v40, 16, v40
	v_lshlrev_b32_e32 v24, 16, v24
	v_mul_f32_e32 v54, 0.5, v16
	v_mul_f32_e32 v43, 0x3fb8aa3b, v43
	v_exp_f32_e32 v42, v42
	v_fma_f32 v16, v53, v16, v16
	v_mul_f32_e32 v28, 0x3fb8aa3b, v28
	v_mul_f32_e32 v34, 0x3f4c422a, v37
	v_fmac_f32_e32 v39, v38, v35
	v_add_f32_e32 v27, v27, v27
	v_mul_f32_e32 v23, 0x3fb8aa3b, v23
	v_lshlrev_b32_e32 v26, 16, v26
	v_mul_f32_e32 v24, 0x3fb8aa3b, v24
	v_exp_f32_e32 v43, v43
	v_mul_f32_e32 v16, 0x3f4c422a, v16
	v_mov_b32_e32 v20, v29
	v_exp_f32_e32 v28, v28
; DI float bf1(const bf16_t* p) { return __uint_as_float((unsigned)(*(GAS const bf16_t*)p) << 16); }
; DI bf16_t tobf(float f) { return (bf16_t)(pk2(f, 0.f) & 0xffffu); }
; DI int otid() { int t = threadIdx.x; asm volatile("" : "+v"(t)); return t; }
; DI int obid() { int b = blockIdx.x; asm volatile("" : "+s"(b)); return b; }
; DI float gelu_tanh(float x) { const float u = 0.7978845608028654f * (x + 0.044715f * x * x * x); const float e = __expf(2.f * u); const float th = 1.f - 2.f / (e + 1.f); return 0.5f * x * (1.f + th); }
; DI void phase_scan2(const bf16_t* A, const bf16_t* U, const float* agg, const bf16_t* GATE, bf16_t* Y) {
;     const int ch = otid();
;     for (int it = obid(); it < 256; it += gridDim.x) {
;         const int b = it >> 4, c = it & 15; const size_t row0 = (size_t)b * TT + (size_t)c * 257; const size_t base = row0 * 512 + ch;
;         float h = 0.f;
;         for (int cc = 0; cc < c; ++cc) { const float Pp = agg[((size_t)(b * 16 + cc) * 512 + ch) * 2], S = agg[((size_t)(b * 16 + cc) * 512 + ch) * 2 + 1]; h = Pp * h + S; }
;         for (int s0 = 0; s0 < 256; s0 += 8) {
;             float a[8], u[8], g[8];
; #pragma unroll
;             for (int e = 0; e < 8; ++e) { a[e] = bf1(A + base + (size_t)(s0 + e) * 512); u[e] = bf1(U + base + (size_t)(s0 + e) * 512); g[e] = bf1(GATE + base + (size_t)(s0 + e) * 512); }
; #pragma unroll
;             for (int e = 0; e < 8; ++e) { h = __expf(a[e]) * h + u[e]; Y[(row0 + s0 + e) * 1024 + 512 + ch] = tobf(gelu_tanh(g[e]) * h); }
;         }
	v_add_f32_e32 v29, v34, v34
	v_mul_f32_e32 v27, 0x3fb8aa3b, v27
	v_fmac_f32_e32 v40, v39, v36
	v_exp_f32_e32 v23, v23
	v_exp_f32_e32 v24, v24
	v_add_f32_e32 v16, v16, v16
	v_mul_f32_e32 v29, 0x3fb8aa3b, v29
	v_exp_f32_e32 v27, v27
	v_fmac_f32_e32 v26, v40, v22
	v_mul_f32_e32 v16, 0x3fb8aa3b, v16
	v_exp_f32_e32 v29, v29
	v_fmac_f32_e32 v21, v26, v17
	v_add_f32_e32 v17, 1.0, v25
	v_add_f32_e32 v22, 1.0, v31
	v_add_f32_e32 v25, 1.0, v33
	v_addc_co_u32_e64 v19, s[6:7], 0, v19, s[6:7]
	v_exp_f32_e32 v16, v16
	v_div_scale_f32 v31, s[6:7], v17, v17, 2.0
	v_fmac_f32_e32 v30, v21, v42
	v_div_scale_f32 v34, s[6:7], v22, v22, 2.0
	v_div_scale_f32 v36, s[6:7], v25, v25, 2.0
	v_add_f32_e32 v28, 1.0, v28
	v_rcp_f32_e32 v47, v31
	v_rcp_f32_e32 v51, v34
	v_fmac_f32_e32 v32, v30, v43
	v_rcp_f32_e32 v43, v36
	v_add_f32_e32 v23, 1.0, v23
	v_mul_f32_e32 v52, 0.5, v41
	v_div_scale_f32 v41, s[6:7], v28, v28, 2.0
	v_add_f32_e32 v27, 1.0, v27
	v_fmac_f32_e32 v20, v32, v24
	v_div_scale_f32 v24, s[14:15], v23, v23, 2.0
	v_rcp_f32_e32 v53, v41
	v_add_f32_e32 v29, 1.0, v29
	v_div_scale_f32 v56, s[14:15], v27, v27, 2.0
	v_rcp_f32_e32 v62, v24
	v_add_f32_e32 v16, 1.0, v16
	v_div_scale_f32 v58, s[16:17], v29, v29, 2.0
	v_rcp_f32_e32 v63, v56
	v_div_scale_f32 v60, s[18:19], v16, v16, 2.0
	v_rcp_f32_e32 v64, v58
	v_fma_f32 v67, -v31, v47, 1.0
	v_fma_f32 v68, -v34, v51, 1.0
	v_fma_f32 v69, -v36, v43, 1.0
	v_div_scale_f32 v33, s[10:11], 2.0, v17, 2.0
	v_div_scale_f32 v35, s[12:13], 2.0, v22, 2.0
	v_div_scale_f32 v37, s[8:9], 2.0, v25, 2.0
	v_rcp_f32_e32 v66, v60
	v_fmac_f32_e32 v47, v67, v47
	v_fmac_f32_e32 v51, v68, v51
	v_fmac_f32_e32 v43, v69, v43
	v_fma_f32 v70, -v41, v53, 1.0
	v_mul_f32_e32 v67, v33, v47
	v_mul_f32_e32 v68, v35, v51
	v_mul_f32_e32 v69, v37, v43
	v_fma_f32 v71, -v24, v62, 1.0
	v_div_scale_f32 v42, s[6:7], 2.0, v28, 2.0
	v_div_scale_f32 v55, vcc, 2.0, v23, 2.0
	v_fmac_f32_e32 v53, v70, v53
	v_fma_f32 v72, -v56, v63, 1.0
	v_fma_f32 v75, -v31, v67, v33
	v_fma_f32 v76, -v34, v68, v35
	v_fma_f32 v77, -v36, v69, v37
	v_fmac_f32_e32 v62, v71, v62
	v_div_scale_f32 v57, s[14:15], 2.0, v27, 2.0
	v_mul_f32_e32 v70, v42, v53
	v_fma_f32 v73, -v58, v64, 1.0
	v_fmac_f32_e32 v63, v72, v63
	v_fmac_f32_e32 v67, v75, v47
	v_fmac_f32_e32 v68, v76, v51
	v_fmac_f32_e32 v69, v77, v43
	v_mul_f32_e32 v71, v55, v62
	v_div_scale_f32 v59, s[16:17], 2.0, v29, 2.0
	v_fma_f32 v74, -v60, v66, 1.0
	v_fma_f32 v78, -v41, v70, v42
	v_fmac_f32_e32 v64, v73, v64
	v_mul_f32_e32 v72, v57, v63
	v_fma_f32 v31, -v31, v67, v33
	v_fma_f32 v33, -v34, v68, v35
	v_fma_f32 v34, -v36, v69, v37
	v_fma_f32 v36, -v24, v71, v55
	v_div_scale_f32 v61, s[18:19], 2.0, v16, 2.0
	v_fmac_f32_e32 v66, v74, v66
	v_fmac_f32_e32 v70, v78, v53
	v_mul_f32_e32 v73, v59, v64
	v_fma_f32 v37, -v56, v72, v57
	v_fmac_f32_e32 v71, v36, v62
	v_mul_f32_e32 v74, v61, v66
	v_fma_f32 v35, -v41, v70, v42
	v_fma_f32 v41, -v58, v73, v59
	v_fmac_f32_e32 v72, v37, v63
	v_fma_f32 v24, -v24, v71, v55
	v_fma_f32 v42, -v60, v74, v61
	v_fmac_f32_e32 v73, v41, v64
	v_fma_f32 v36, -v56, v72, v57
	v_div_fmas_f32 v24, v24, v62, v71
	s_mov_b64 vcc, s[14:15]
	v_fmac_f32_e32 v74, v42, v66
	v_fma_f32 v37, -v58, v73, v59
	v_div_fixup_f32 v23, v24, v23, 2.0
	v_div_fmas_f32 v24, v36, v63, v72
	s_mov_b64 vcc, s[16:17]
	v_fma_f32 v41, -v60, v74, v61
	v_sub_f32_e32 v23, 1.0, v23
	v_div_fixup_f32 v24, v24, v27, 2.0
	v_div_fmas_f32 v27, v37, v64, v73
	s_mov_b64 vcc, s[18:19]
	v_add_f32_e32 v23, 1.0, v23
	v_sub_f32_e32 v24, 1.0, v24
	v_div_fixup_f32 v27, v27, v29, 2.0
	v_div_fmas_f32 v29, v41, v66, v74
	s_mov_b64 vcc, s[10:11]
	v_mul_f32_e32 v23, v45, v23
	v_add_f32_e32 v24, 1.0, v24
	v_sub_f32_e32 v27, 1.0, v27
	v_div_fixup_f32 v16, v29, v16, 2.0
	v_div_fmas_f32 v29, v31, v47, v67
	s_mov_b64 vcc, s[12:13]
	v_mul_f32_e32 v23, v38, v23
	v_mul_f32_e32 v24, v49, v24
	v_add_f32_e32 v27, 1.0, v27
	v_sub_f32_e32 v16, 1.0, v16
	v_div_fixup_f32 v17, v29, v17, 2.0
	v_div_fmas_f32 v29, v33, v51, v68
	s_mov_b64 vcc, s[8:9]
	v_cvt_pk_bf16_f32 v23, v23, s0
	v_mul_f32_e32 v24, v39, v24
	v_mul_f32_e32 v27, v52, v27
	v_add_f32_e32 v16, 1.0, v16
	v_sub_f32_e32 v17, 1.0, v17
	v_div_fixup_f32 v22, v29, v22, 2.0
	v_div_fmas_f32 v29, v34, v43, v69
	s_mov_b64 vcc, s[6:7]
	global_store_short v[14:15], v23, off offset:1024
	v_cvt_pk_bf16_f32 v23, v24, s0
	v_mul_f32_e32 v24, v40, v27
	v_mul_f32_e32 v16, v54, v16
	v_add_f32_e32 v17, 1.0, v17
	v_sub_f32_e32 v22, 1.0, v22
	v_div_fixup_f32 v25, v29, v25, 2.0
	v_div_fmas_f32 v27, v35, v53, v70
	global_store_short v[14:15], v23, off offset:3072
	v_cvt_pk_bf16_f32 v14, v24, s0
	v_mul_f32_e32 v15, v26, v16
	v_mul_f32_e32 v16, v44, v17
	v_add_f32_e32 v17, 1.0, v22
	v_sub_f32_e32 v22, 1.0, v25
	v_div_fixup_f32 v23, v27, v28, 2.0
	global_store_short v[12:13], v14, off offset:1024
	v_cvt_pk_bf16_f32 v14, v15, s0
	v_mul_f32_e32 v15, v21, v16
	v_mul_f32_e32 v16, v46, v17
	v_add_f32_e32 v17, 1.0, v22
	v_sub_f32_e32 v21, 1.0, v23
	global_store_short v[12:13], v14, off offset:3072
	v_cvt_pk_bf16_f32 v12, v15, s0
	v_mul_f32_e32 v13, v30, v16
	v_mul_f32_e32 v14, v48, v17
	v_add_f32_e32 v15, 1.0, v21
	global_store_short v[10:11], v12, off offset:1024
	v_cvt_pk_bf16_f32 v12, v13, s0
	v_mul_f32_e32 v13, v32, v14
	v_mul_f32_e32 v14, v50, v15
	global_store_short v[10:11], v12, off offset:3072
	v_cvt_pk_bf16_f32 v10, v13, s0
	v_mul_f32_e32 v11, v20, v14
	global_store_short v[18:19], v10, off offset:1024
	v_cvt_pk_bf16_f32 v10, v11, s0
	global_store_short v[18:19], v10, off offset:3072
	s_cbranch_scc1 .LBB0_124
; DI float bf1(const bf16_t* p) { return __uint_as_float((unsigned)(*(GAS const bf16_t*)p) << 16); }
; DI bf16_t tobf(float f) { return (bf16_t)(pk2(f, 0.f) & 0xffffu); }
; DI float gelu_tanh(float x) { const float u = 0.7978845608028654f * (x + 0.044715f * x * x * x); const float e = __expf(2.f * u); const float th = 1.f - 2.f / (e + 1.f); return 0.5f * x * (1.f + th); }
; DI void phase_scan2(const bf16_t* A, const bf16_t* U, const float* agg, const bf16_t* GATE, bf16_t* Y) {
;     ...
;         { const float a = bf1(A + base + (size_t)256 * 512), u = bf1(U + base + (size_t)256 * 512), g = bf1(GATE + base + (size_t)256 * 512); h = __expf(a) * h + u; Y[(row0 + 256) * 1024 + 512 + ch] = tobf(gelu_tanh(g) * h); }
	s_mul_hi_i32 s6, s5, 0x1010
	s_mulk_i32 s5, 0x1010
	s_mulk_i32 s4, 0x101
	s_add_u32 s4, s5, s4
	s_addc_u32 s5, s6, 0
	s_lshl_b64 s[6:7], s[4:5], 9
	v_lshl_add_u64 v[6:7], s[6:7], 0, v[0:1]
	v_lshlrev_b64 v[6:7], 1, v[6:7]
	v_lshl_add_u64 v[8:9], s[28:29], 0, v[6:7]
	s_mov_b32 s6, 0x40000
	v_add_co_u32_e32 v8, vcc, s6, v8
	v_lshl_add_u64 v[10:11], s[38:39], 0, v[6:7]
	s_nop 0
	v_addc_co_u32_e32 v9, vcc, 0, v9, vcc
	v_add_co_u32_e32 v10, vcc, s6, v10
	v_lshl_add_u64 v[6:7], s[36:37], 0, v[6:7]
	s_nop 0
	v_addc_co_u32_e32 v11, vcc, 0, v11, vcc
	v_add_co_u32_e32 v6, vcc, s6, v6
	s_lshl_b64 s[4:5], s[4:5], 11
	s_nop 0
	v_addc_co_u32_e32 v7, vcc, 0, v7, vcc
	global_load_ushort v8, v[8:9], off
	s_nop 0
	global_load_ushort v9, v[10:11], off
	s_nop 0
	global_load_ushort v10, v[6:7], off
	s_add_u32 s4, s40, s4
	s_addc_u32 s5, s41, s5
	v_lshl_add_u64 v[6:7], v[0:1], 1, s[4:5]
	s_add_i32 s1, s1, s62
	s_add_i32 s0, s0, s62
	s_cmpk_gt_i32 s1, 0xff
	s_waitcnt vmcnt(0)
	v_lshlrev_b32_e32 v8, 16, v8
	v_mul_f32_e32 v8, 0x3fb8aa3b, v8
	v_lshlrev_b32_e32 v10, 16, v10
	v_mul_f32_e32 v11, 0x3d372713, v10
	v_mul_f32_e32 v11, v11, v10
	v_fma_f32 v11, v11, v10, v10
	v_mul_f32_e32 v11, 0x3f4c422a, v11
	v_add_f32_e32 v11, v11, v11
	v_mul_f32_e32 v11, 0x3fb8aa3b, v11
	v_exp_f32_e32 v11, v11
	v_exp_f32_e32 v8, v8
	v_lshlrev_b32_e32 v9, 16, v9
	v_mul_f32_e32 v10, 0.5, v10
	v_add_f32_e32 v11, 1.0, v11
	v_div_scale_f32 v12, s[4:5], v11, v11, -2.0
	v_rcp_f32_e32 v13, v12
	v_fmac_f32_e32 v9, v20, v8
	v_div_scale_f32 v8, vcc, -2.0, v11, -2.0
	v_fma_f32 v14, -v12, v13, 1.0
	v_fmac_f32_e32 v13, v14, v13
	v_mul_f32_e32 v14, v8, v13
	v_fma_f32 v15, -v12, v14, v8
	v_fmac_f32_e32 v14, v15, v13
	v_fma_f32 v8, -v12, v14, v8
	v_div_fmas_f32 v8, v8, v13, v14
	v_div_fixup_f32 v8, v8, v11, -2.0
	v_add_f32_e32 v8, 1.0, v8
	v_add_f32_e32 v8, 1.0, v8
	v_mul_f32_e32 v8, v10, v8
	v_add_co_u32_e32 v6, vcc, 0x80000, v6
	v_mul_f32_e32 v8, v9, v8
	s_nop 0
	v_addc_co_u32_e32 v7, vcc, 0, v7, vcc
	v_cvt_pk_bf16_f32 v8, v8, s0
	global_store_short v[6:7], v8, off offset:1024
	s_cbranch_scc0 .LBB0_119

; DI float bf1(const bf16_t* p) { return __uint_as_float((unsigned)(*(GAS const bf16_t*)p) << 16); }
; DI int obid() { int b = blockIdx.x; asm volatile("" : "+s"(b)); return b; }
; DI void phase_scan1(const bf16_t* A, const bf16_t* U, float* agg) {
;     ...
;     for (int it = obid(); it < 256; it += gridDim.x) {
;         const int b = it >> 4, c = it & 15; const size_t base = ((size_t)b * TT + (size_t)c * 257) * 512 + ch;
;         float Pl = 0.f, S = 0.f;
;         for (int s0 = 0; s0 < 256; s0 += 8) {
;             float a[8], u[8];
; #pragma unroll
;             for (int e = 0; e < 8; ++e) { a[e] = bf1(A + base + (size_t)(s0 + e) * 512); u[e] = bf1(U + base + (size_t)(s0 + e) * 512); }
; #pragma unroll
;             for (int e = 0; e < 8; ++e) { S = __expf(a[e]) * S + u[e]; Pl += a[e]; }
;         }
;         { const float a = bf1(A + base + (size_t)256 * 512), u = bf1(U + base + (size_t)256 * 512); S = __expf(a) * S + u; Pl += a; }
;         agg[((size_t)it * 512 + ch) * 2] = __expf(Pl); agg[((size_t)it * 512 + ch) * 2 + 1] = S;
;     }
.LBB0_132:
	v_add_co_u32_e32 v8, vcc, 0xf7f7f000, v6
	global_load_ushort v14, v[6:7], off offset:-4096
	global_load_ushort v15, v[6:7], off offset:-3072
	global_load_ushort v16, v[6:7], off offset:-2048
	global_load_ushort v17, v[6:7], off offset:-1024
	global_load_ushort v18, v[6:7], off
	v_addc_co_u32_e32 v9, vcc, -1, v7, vcc
	v_add_co_u32_e32 v10, vcc, 0xfffff000, v6
	s_add_i32 s7, s7, 8
	s_nop 0
	v_addc_co_u32_e32 v11, vcc, -1, v7, vcc
	v_add_co_u32_e32 v12, vcc, 0xf7f80000, v6
	s_waitcnt lgkmcnt(0)
	global_load_ushort v19, v[8:9], off offset:-3072
	global_load_ushort v20, v[8:9], off offset:-1024
	global_load_ushort v21, v[10:11], off offset:-3072
	global_load_ushort v22, v[10:11], off offset:-2048
	s_nop 0
	global_load_ushort v11, v[10:11], off offset:-1024
	v_addc_co_u32_e32 v13, vcc, -1, v7, vcc
	global_load_ushort v23, v[12:13], off offset:-3072
	global_load_ushort v24, v[12:13], off offset:-1024
	global_load_ushort v25, v[8:9], off
	s_nop 0
	global_load_ushort v9, v[8:9], off offset:-2048
	s_nop 0
	global_load_ushort v26, v[12:13], off
	s_nop 0
	global_load_ushort v13, v[12:13], off offset:-2048
	s_cmpk_lt_u32 s7, 0xf8
	v_lshl_add_u64 v[6:7], v[6:7], 0, s[74:75]
	v_add_co_u32_e32 v40, vcc, 0xf7f7f000, v6
	global_load_ushort v46, v[6:7], off offset:-4096
	global_load_ushort v47, v[6:7], off offset:-3072
	global_load_ushort v48, v[6:7], off offset:-2048
	global_load_ushort v49, v[6:7], off offset:-1024
	global_load_ushort v50, v[6:7], off
	v_addc_co_u32_e32 v41, vcc, -1, v7, vcc
	v_add_co_u32_e32 v42, vcc, 0xfffff000, v6
	s_add_i32 s7, s7, 8
	s_nop 0
	v_addc_co_u32_e32 v43, vcc, -1, v7, vcc
	v_add_co_u32_e32 v44, vcc, 0xf7f80000, v6
	s_waitcnt lgkmcnt(0)
	global_load_ushort v51, v[40:41], off offset:-3072
	global_load_ushort v52, v[40:41], off offset:-1024
	global_load_ushort v53, v[42:43], off offset:-3072
	global_load_ushort v54, v[42:43], off offset:-2048
	s_nop 0
	global_load_ushort v43, v[42:43], off offset:-1024
	v_addc_co_u32_e32 v45, vcc, -1, v7, vcc
	global_load_ushort v55, v[44:45], off offset:-3072
	global_load_ushort v56, v[44:45], off offset:-1024
	global_load_ushort v57, v[40:41], off
	s_nop 0
	global_load_ushort v41, v[40:41], off offset:-2048
	s_nop 0
	global_load_ushort v58, v[44:45], off
	s_nop 0
	global_load_ushort v45, v[44:45], off offset:-2048
	s_cmpk_lt_u32 s7, 0xf8
	v_lshl_add_u64 v[6:7], v[6:7], 0, s[74:75]
	s_waitcnt vmcnt(16)
	v_lshlrev_b32_e32 v27, 16, v14
	v_lshlrev_b32_e32 v8, 16, v15
	v_lshlrev_b32_e32 v10, 16, v16
	v_lshlrev_b32_e32 v12, 16, v17
	v_lshlrev_b32_e32 v14, 16, v18
	v_lshlrev_b32_e32 v15, 16, v19
	v_lshlrev_b32_e32 v17, 16, v20
	v_lshlrev_b32_e32 v19, 16, v23
	v_add_f32_e32 v5, v5, v15
	v_lshlrev_b32_e32 v29, 16, v11
	v_mul_f32_e32 v11, 0x3fb8aa3b, v15
	v_lshlrev_b32_e32 v9, 16, v9
	v_exp_f32_e32 v23, v11
	v_mul_f32_e32 v20, 0x3fb8aa3b, v9
	v_mul_f32_e32 v15, 0x3fb8aa3b, v17
	v_lshlrev_b32_e32 v11, 16, v25
	v_exp_f32_e32 v32, v20
	v_lshlrev_b32_e32 v28, 16, v21
	v_lshlrev_b32_e32 v21, 16, v24
	v_exp_f32_e32 v24, v15
	v_mul_f32_e32 v25, 0x3fb8aa3b, v11
	v_mul_f32_e32 v16, 0x3fb8aa3b, v19
	v_exp_f32_e32 v25, v25
	v_lshlrev_b32_e32 v22, 16, v22
	v_lshlrev_b32_e32 v13, 16, v13
	v_exp_f32_e32 v31, v16
	v_fmac_f32_e32 v28, v4, v23
	v_lshlrev_b32_e32 v15, 16, v26
	v_mul_f32_e32 v26, 0x3fb8aa3b, v13
	v_fmac_f32_e32 v22, v28, v32
	v_exp_f32_e32 v16, v26
	v_fmac_f32_e32 v29, v22, v24
	v_fmac_f32_e32 v27, v29, v25
	v_mul_f32_e32 v18, 0x3fb8aa3b, v21
	v_mul_f32_e32 v4, v27, v31
	v_exp_f32_e32 v18, v18
	v_pk_add_f32 v[4:5], v[4:5], v[8:9]
	v_mul_f32_e32 v30, 0x3fb8aa3b, v15
	v_pk_mul_f32 v[8:9], v[4:5], v[16:17]
	v_pk_add_f32 v[4:5], v[4:5], v[16:17]
	v_exp_f32_e32 v20, v30
	v_mov_b32_e32 v9, v5
	v_pk_add_f32 v[4:5], v[8:9], v[10:11]
	s_nop 0
	v_pk_mul_f32 v[8:9], v[4:5], v[18:19]
	v_pk_add_f32 v[4:5], v[4:5], v[18:19]
	s_nop 0
	v_mov_b32_e32 v9, v5
	v_pk_add_f32 v[4:5], v[8:9], v[12:13]
	s_nop 0
	v_pk_mul_f32 v[8:9], v[4:5], v[20:21]
	v_pk_add_f32 v[4:5], v[4:5], v[20:21]
	s_nop 0
	v_mov_b32_e32 v9, v5
	v_pk_add_f32 v[4:5], v[8:9], v[14:15]
	s_waitcnt vmcnt(0)
	v_lshlrev_b32_e32 v27, 16, v46
	v_lshlrev_b32_e32 v8, 16, v47
	v_lshlrev_b32_e32 v10, 16, v48
	v_lshlrev_b32_e32 v12, 16, v49
	v_lshlrev_b32_e32 v14, 16, v50
	v_lshlrev_b32_e32 v15, 16, v51
	v_lshlrev_b32_e32 v17, 16, v52
	v_lshlrev_b32_e32 v19, 16, v55
	v_add_f32_e32 v5, v5, v15
	v_lshlrev_b32_e32 v29, 16, v43
	v_mul_f32_e32 v11, 0x3fb8aa3b, v15
	v_lshlrev_b32_e32 v9, 16, v41
	v_exp_f32_e32 v23, v11
	v_mul_f32_e32 v20, 0x3fb8aa3b, v9
	v_mul_f32_e32 v15, 0x3fb8aa3b, v17
	v_lshlrev_b32_e32 v11, 16, v57
	v_exp_f32_e32 v32, v20
	v_lshlrev_b32_e32 v28, 16, v53
	v_lshlrev_b32_e32 v21, 16, v56
	v_exp_f32_e32 v24, v15
	v_mul_f32_e32 v25, 0x3fb8aa3b, v11
	v_mul_f32_e32 v16, 0x3fb8aa3b, v19
	v_exp_f32_e32 v25, v25
	v_lshlrev_b32_e32 v22, 16, v54
	v_lshlrev_b32_e32 v13, 16, v45
	v_exp_f32_e32 v31, v16
	v_fmac_f32_e32 v28, v4, v23
	v_lshlrev_b32_e32 v15, 16, v58
	v_mul_f32_e32 v26, 0x3fb8aa3b, v13
	v_fmac_f32_e32 v22, v28, v32
	v_exp_f32_e32 v16, v26
	v_fmac_f32_e32 v29, v22, v24
	v_fmac_f32_e32 v27, v29, v25
	v_mul_f32_e32 v18, 0x3fb8aa3b, v21
	v_mul_f32_e32 v4, v27, v31
	v_exp_f32_e32 v18, v18
	v_pk_add_f32 v[4:5], v[4:5], v[8:9]
	v_mul_f32_e32 v30, 0x3fb8aa3b, v15
	v_pk_mul_f32 v[8:9], v[4:5], v[16:17]
	v_pk_add_f32 v[4:5], v[4:5], v[16:17]
	v_exp_f32_e32 v20, v30
	v_mov_b32_e32 v9, v5
	v_pk_add_f32 v[4:5], v[8:9], v[10:11]
	s_nop 0
	v_pk_mul_f32 v[8:9], v[4:5], v[18:19]
	v_pk_add_f32 v[4:5], v[4:5], v[18:19]
	s_nop 0
	v_mov_b32_e32 v9, v5
	v_pk_add_f32 v[4:5], v[8:9], v[12:13]
	s_nop 0
	v_pk_mul_f32 v[8:9], v[4:5], v[20:21]
	v_pk_add_f32 v[4:5], v[4:5], v[20:21]
	s_nop 0
	v_mov_b32_e32 v9, v5
	v_pk_add_f32 v[4:5], v[8:9], v[14:15]
	s_cbranch_scc1 .LBB0_132
	s_and_b32 s7, s4, 15
	s_mul_hi_i32 s9, s5, 0x1010
	s_mulk_i32 s5, 0x1010
	s_mulk_i32 s7, 0x101
	s_add_u32 s8, s5, s7
	s_addc_u32 s9, s9, 0
	s_lshl_b64 s[8:9], s[8:9], 9
	v_lshl_add_u64 v[6:7], s[8:9], 0, v[0:1]
	v_lshlrev_b64 v[6:7], 1, v[6:7]
	v_lshl_add_u64 v[8:9], s[28:29], 0, v[6:7]
	s_mov_b32 s5, 0x40000
	v_add_co_u32_e32 v8, vcc, s5, v8
	v_lshl_add_u64 v[6:7], s[38:39], 0, v[6:7]
	s_nop 0
	v_addc_co_u32_e32 v9, vcc, 0, v9, vcc
	global_load_ushort v8, v[8:9], off
	v_add_co_u32_e32 v6, vcc, s5, v6
	s_ashr_i32 s5, s4, 31
	s_nop 0
	v_addc_co_u32_e32 v7, vcc, 0, v7, vcc
	global_load_ushort v9, v[6:7], off
	s_add_i32 s6, s6, s62
	s_lshl_b64 s[8:9], s[4:5], 12
	s_add_i32 s4, s4, s62
	v_lshl_add_u64 v[6:7], v[2:3], 0, s[8:9]
	s_cmpk_gt_i32 s4, 0xff
	s_waitcnt vmcnt(1)
	v_lshlrev_b32_e32 v8, 16, v8
	v_mul_f32_e32 v10, 0x3fb8aa3b, v8
	v_add_f32_e32 v5, v5, v8
	v_exp_f32_e32 v10, v10
	v_mul_f32_e32 v5, 0x3fb8aa3b, v5
	v_exp_f32_e32 v8, v5
	s_waitcnt vmcnt(0)
	v_lshlrev_b32_e32 v9, 16, v9
	v_fmac_f32_e32 v9, v4, v10
	global_store_dwordx2 v[6:7], v[8:9], off
	s_cbranch_scc0 .LBB0_131

;     __device__ __forceinline__ void operator()(const f32x4 (&acc)[2][2][4][2], const Unit& u, int wr, int wc, int fr, int fq) const {
;     ...
;         else { if (acc[0][0][0][0][0] == 123456.789f) *(float*)p0 = 1.f; }
.LBB0_502:
	s_and_b64 vcc, exec, s[66:67]
	s_cbranch_vccz .LBB0_507
	s_mov_b32 s6, 0x47f12065
	v_cmp_eq_f32_e32 vcc, s6, v128
	s_and_saveexec_b64 s[6:7], vcc
	s_cbranch_execz .LBB0_505
	v_mov_b64_e32 v[66:67], s[86:87]
	v_mov_b32_e32 v64, 1.0
	global_store_dword v[66:67], v64, off
